# speedup vs baseline: 1.0508x; 1.0004x over previous
; __device__ __forceinline__ f32x4 mfma16(bf16x8 a, bf16x8 b, f32x4 c) { return __builtin_amdgcn_mfma_f32_16x16x32_f16(__builtin_bit_cast(f16x8, a), __builtin_bit_cast(f16x8, b), c, 0, 0, 0); }
; __device__ __forceinline__ void wave_lds_fence() { asm volatile("s_waitcnt lgkmcnt(0)" ::: "memory"); __builtin_amdgcn_wave_barrier(); }
; __device__ __forceinline__ void ssm_proj16(const SsmProj& P, u32x4 uw, float* X, int fr, int fq) {
;     const bf16x8 uf = __builtin_bit_cast(bf16x8, uw);
; #pragma unroll
;     for (int nt = 0; nt < 8; ++nt) { f32x4 d = mfma16(uf, P.bf[nt], (f32x4){0.f, 0.f, 0.f, 0.f}); asm volatile("" :: "v"(uf), "v"(P.bf[nt]), "v"(d));
; #pragma unroll
;         for (int r = 0; r < 4; ++r) X[(4 * fq + r) * 132 + 16 * nt + fr] = d[r]; }
; }
; __device__ __forceinline__ void phase_ssm2(int wid_s, unsigned char* shm, const float* US, const float* SSA, const float* SSB, const float* FIN, const float* c_re, const float* c_im, const float* dvec, bf16_t* YG) {
;     ...
;         for (int sub = 0; sub < 4; ++sub) {
;             const size_t tok0 = (size_t)b * SEQ + ch * LCH + sub * 16;
;             wave_lds_fence();
;             ssm_proj16(P, uw, X, fr, fq);
;             if (sub < 3) uw = ssm_u_load(US, tok0 + 16, g, fr, fq);
;             const u32x2 uh = *(const u32x2*)((const bf16_t*)US + (tok0 + fr) * 512 + g * 16 + 4 * fq);
;             wave_lds_fence();
.LBB0_495:
	s_waitcnt lgkmcnt(0)
	v_mfma_f32_16x16x32_f16 v[62:65], v[76:79], v[8:11], 0
	v_add_u32_e32 v3, 0x400, v107
	s_waitcnt lgkmcnt(0)
	s_cmp_eq_u32 s18, 3
	s_cselect_b64 vcc, -1, 0
	s_nop 4
	ds_write2_b32 v107, v62, v63 offset1:132
	ds_write2_b32 v3, v64, v65 offset0:8 offset1:140
	v_mfma_f32_16x16x32_f16 v[62:65], v[76:79], v[12:15], 0
	s_nop 7
	ds_write2_b32 v107, v62, v63 offset0:16 offset1:148
	ds_write2_b32 v3, v64, v65 offset0:24 offset1:156
	v_mfma_f32_16x16x32_f16 v[62:65], v[76:79], v[4:7], 0
	s_nop 7
	ds_write2_b32 v107, v62, v63 offset0:32 offset1:164
	ds_write2_b32 v3, v64, v65 offset0:40 offset1:172
	v_mfma_f32_16x16x32_f16 v[62:65], v[76:79], v[16:19], 0
	s_nop 7
	ds_write2_b32 v107, v62, v63 offset0:48 offset1:180
	ds_write2_b32 v3, v64, v65 offset0:56 offset1:188
	v_mfma_f32_16x16x32_f16 v[62:65], v[76:79], v[24:27], 0
	s_nop 7
	ds_write2_b32 v107, v62, v63 offset0:64 offset1:196
	ds_write2_b32 v3, v64, v65 offset0:72 offset1:204
	v_mfma_f32_16x16x32_f16 v[62:65], v[76:79], v[28:31], 0
	s_nop 7
	ds_write2_b32 v107, v62, v63 offset0:80 offset1:212
	ds_write2_b32 v3, v64, v65 offset0:88 offset1:220
	v_mfma_f32_16x16x32_f16 v[62:65], v[76:79], v[20:23], 0
	s_nop 7
	ds_write2_b32 v107, v62, v63 offset0:96 offset1:228
	ds_write2_b32 v3, v64, v65 offset0:104 offset1:236
	v_mfma_f32_16x16x32_f16 v[62:65], v[76:79], v[32:35], 0
	v_lshl_or_b32 v48, s18, 4, v102
	v_mov_b32_e32 v49, v103
	v_cndmask_b32_e32 v79, 0, v79, vcc
	s_nor_b64 s[20:21], s[2:3], vcc
	v_cndmask_b32_e32 v78, 0, v78, vcc
	v_cndmask_b32_e32 v77, 0, v77, vcc
	v_cndmask_b32_e32 v76, 0, v76, vcc
	s_nop 0
	ds_write2_b32 v107, v62, v63 offset0:112 offset1:244
	ds_write2_b32 v3, v64, v65 offset0:120 offset1:252
	s_and_saveexec_b64 s[6:7], s[20:21]
	s_cbranch_execz .LBB0_497
	v_lshl_add_u64 v[50:51], v[48:49], 0, v[94:95]
	v_lshlrev_b64 v[50:51], 10, v[50:51]
	v_lshl_add_u64 v[50:51], v[0:1], 0, v[50:51]
	global_load_dwordx4 v[76:79], v[50:51], off
.LBB0_497:
	s_or_b64 exec, exec, s[6:7]
	v_or_b32_e32 v48, v48, v80
	v_lshlrev_b64 v[50:51], 10, v[48:49]
	v_lshl_add_u64 v[50:51], v[42:43], 0, v[50:51]
	global_load_dwordx2 v[64:65], v[50:51], off
	s_waitcnt lgkmcnt(0)
	v_lshlrev_b64 v[62:63], 9, v[48:49]
	s_mov_b32 s6, 16
	v_mov_b32_e32 v3, v110
	v_mov_b32_e32 v48, v109
